# grid barrier: each workgroup issues the L2 write-back when it arrives (leader fence kept)
# baseline (speedup 1.0000x reference)
; __device__ __forceinline__ unsigned xb_add(unsigned* p, unsigned v) { asm volatile("" : "+v"(p)); return __hip_atomic_fetch_add(p, v, __ATOMIC_RELAXED, __HIP_MEMORY_SCOPE_AGENT); }
; __device__ __forceinline__ void xcd_barrier(const XcdBarrier& b, int tid) {
;     ...
;     if (tid == 0) {
;         unsigned* bar = b.bar;
;         __builtin_amdgcn_s_waitcnt(0);
;         unsigned nloc = b.st[0], nx = b.st[1];
;         if (nloc == 0u) { xcd_barrier_complete(bar, b.x, nloc, nx); b.st[0] = nloc; b.st[1] = nx; }
;         const unsigned old = xb_add(&bar[XB_XSUB(b.x)], 1u);
;         const unsigned gen = old / nloc;
;         if (old + 1u == (gen + 1u) * nloc) {
.LBB0_166:
	v_readlane_b32 s4, v253, 26
	v_readlane_b32 s5, v253, 27
	v_cvt_f32_u32_e32 v3, v2
	v_rcp_iflag_f32_e32 v3, v3
	v_mov_b64_e32 v[4:5], s[4:5]
	buffer_wbl2 sc1
	flat_atomic_add v1, v[4:5], v251 sc0
	v_mul_f32_e32 v3, 0x4f7ffffe, v3
	v_cvt_u32_f32_e32 v3, v3
	v_sub_u32_e32 v4, 0, v2
	v_mul_lo_u32 v4, v4, v3
	v_mul_hi_u32 v4, v3, v4
	v_add_u32_e32 v3, v3, v4
	s_waitcnt vmcnt(0) lgkmcnt(0)
	v_mul_hi_u32 v3, v1, v3
	v_mul_lo_u32 v5, v3, v2
	v_add_u32_e32 v4, 1, v1
	v_sub_u32_e32 v1, v1, v5
	v_add_u32_e32 v6, 1, v3
	v_cmp_ge_u32_e32 vcc, v1, v2
	v_sub_u32_e32 v5, v1, v2
	s_nop 0
	v_cndmask_b32_e32 v3, v3, v6, vcc
	v_cndmask_b32_e32 v1, v1, v5, vcc
	v_add_u32_e32 v5, 1, v3
	v_cmp_ge_u32_e32 vcc, v1, v2
	s_nop 1
	v_cndmask_b32_e32 v1, v3, v5, vcc
	v_mad_u64_u32 v[2:3], s[4:5], v2, v1, v[2:3]
	v_cmp_ne_u32_e32 vcc, v4, v2
	s_and_saveexec_b64 s[4:5], vcc
	s_xor_b64 s[24:25], exec, s[4:5]
	s_cbranch_execz .LBB0_180
	s_mov_b32 s0, 1
	s_mov_b64 s[38:39], 0
	s_branch .LBB0_170

; __device__ __forceinline__ unsigned xb_add(unsigned* p, unsigned v) { asm volatile("" : "+v"(p)); return __hip_atomic_fetch_add(p, v, __ATOMIC_RELAXED, __HIP_MEMORY_SCOPE_AGENT); }
; __device__ __forceinline__ void xcd_barrier(const XcdBarrier& b, int tid) {
;     ...
;     if (tid == 0) {
;         unsigned* bar = b.bar;
;         __builtin_amdgcn_s_waitcnt(0);
;         unsigned nloc = b.st[0], nx = b.st[1];
;         if (nloc == 0u) { xcd_barrier_complete(bar, b.x, nloc, nx); b.st[0] = nloc; b.st[1] = nx; }
;         const unsigned old = xb_add(&bar[XB_XSUB(b.x)], 1u);
;         const unsigned gen = old / nloc;
;         if (old + 1u == (gen + 1u) * nloc) {
.LBB0_234:
	v_readlane_b32 s4, v253, 26
	v_readlane_b32 s5, v253, 27
	v_cvt_f32_u32_e32 v1, v2
	v_rcp_iflag_f32_e32 v1, v1
	v_mov_b64_e32 v[4:5], s[4:5]
	buffer_wbl2 sc1
	flat_atomic_add v3, v[4:5], v251 sc0
	v_mul_f32_e32 v1, 0x4f7ffffe, v1
	v_cvt_u32_f32_e32 v1, v1
	v_sub_u32_e32 v4, 0, v2
	v_mul_lo_u32 v4, v4, v1
	v_mul_hi_u32 v4, v1, v4
	v_add_u32_e32 v1, v1, v4
	s_waitcnt vmcnt(0) lgkmcnt(0)
	v_mul_hi_u32 v1, v3, v1
	v_mul_lo_u32 v4, v1, v2
	v_sub_u32_e32 v4, v3, v4
	v_cmp_ge_u32_e32 vcc, v4, v2
	v_add_u32_e32 v5, 1, v1
	s_nop 0
	v_cndmask_b32_e32 v1, v1, v5, vcc
	v_sub_u32_e32 v5, v4, v2
	v_cndmask_b32_e32 v4, v4, v5, vcc
	v_cmp_ge_u32_e32 vcc, v4, v2
	v_add_u32_e32 v4, 1, v1
	s_nop 0
	v_cndmask_b32_e32 v1, v1, v4, vcc
	v_add_u32_e32 v4, 1, v3
	v_mad_u64_u32 v[2:3], s[4:5], v2, v1, v[2:3]
	v_cmp_ne_u32_e32 vcc, v4, v2
	s_and_saveexec_b64 s[4:5], vcc
	s_xor_b64 s[24:25], exec, s[4:5]
	s_cbranch_execz .LBB0_248
	s_mov_b32 s0, 1
	s_mov_b64 s[38:39], 0
	s_branch .LBB0_238
